# nt hint also on the read-once q/k row loads of the ret prep phase
# speedup vs baseline: 1.0246x; 1.0018x over previous
; DI float ret_lg(int h) { return log1pf(-exp2f(-5.f - (float)h)); }
; DI void phase_ret_prep(const Params& p, unsigned char* smem) {
;     ...
;     for (int item = blockIdx.x; item < 1024; item += gridDim.x) {
;         const int n = item & 31, h = (item >> 5) & 3, b = item >> 7;
;         const int tok0 = b * 2048 + n * 64;
;         const float lg = ret_lg(h);
;         unsigned char* blk = p.ws + WS_ROP + (size_t)item * ROP_STRIDE;
;         bf16_t* o_qd = (bf16_t*)blk; bf16_t* o_kdT = o_qd + 16384; bf16_t* o_qkD = o_kdT + 16384; bf16_t* o_vT = o_qkD + 4096;
; #pragma unroll
;         for (int m = 0; m < 2; ++m) {
;             const int e = tid + 512 * m, row = e >> 4, i0 = (e & 15) * 8;
;             const bf16_t* src = P1 + (size_t)(tok0 + row) * LDP1 + h * 256 + i0;
;             const u32x4 q1 = *(const u32x4*)src, q2 = *(const u32x4*)(src + 128), k1 = *(const u32x4*)(src + 1024), k2 = *(const u32x4*)(src + 1152);
;             const unsigned q1u[4] = {q1.x, q1.y, q1.z, q1.w}, q2u[4] = {q2.x, q2.y, q2.z, q2.w}, k1u[4] = {k1.x, k1.y, k1.z, k1.w}, k2u[4] = {k2.x, k2.y, k2.z, k2.w};
;             float qa[8], qb[8], ka[8], kb[8];
; #pragma unroll
;             for (int j = 0; j < 8; ++j) {
;                 const f32x2 tr = tabR[row * 128 + i0 + j], tc = tabC[n * 128 + i0 + j];
.LBB0_1268:
	s_and_b32 s43, s58, 31
	s_bfe_u32 s54, s58, 0x20005
	s_lshl_b32 s42, s58, 4
	s_and_b32 s42, s42, 0xfffff800
	s_lshl_b32 s55, s43, 6
	v_cvt_f32_ubyte0_e32 v2, s54
	s_or_b32 s42, s42, s55
	v_sub_f32_e32 v2, 0xc0a00000, v2
	s_mov_b32 s55, 0xc2fc0000
	v_cmp_gt_f32_e32 vcc, s55, v2
	s_and_b64 s[72:73], vcc, exec
	s_cselect_b32 s55, 0xffffffc0, 0
	v_cndmask_b32_e32 v3, 0, v130, vcc
	v_add_f32_e32 v2, v2, v3
	v_exp_f32_e32 v2, v2
	s_mul_i32 s59, s58, 0x22000
	s_add_u32 s72, s60, s59
	v_lshlrev_b32_e32 v22, 3, v102
	v_ldexp_f32 v18, v2, s55
	v_sub_f32_e32 v4, 1.0, v18
	v_add_f32_e32 v2, -1.0, v4
	v_sub_f32_e32 v3, v2, v4
	v_add_f32_e32 v3, 1.0, v3
	v_sub_f32_e64 v2, -v18, v2
	v_add_f32_e32 v5, v2, v3
	v_frexp_mant_f32_e32 v2, v4
	s_mov_b32 s55, 0x3f2aaaab
	v_cmp_gt_f32_e32 vcc, s55, v2
	v_cvt_f64_f32_e32 v[2:3], v4
	v_frexp_exp_i32_f64_e32 v2, v[2:3]
	v_subbrev_co_u32_e32 v10, vcc, 0, v2, vcc
	v_sub_u32_e32 v2, 0, v10
	v_ldexp_f32 v3, v4, v2
	v_add_f32_e32 v4, -1.0, v3
	v_add_f32_e32 v6, 1.0, v3
	v_ldexp_f32 v2, v5, v2
	v_add_f32_e32 v5, 1.0, v4
	v_add_f32_e32 v7, -1.0, v6
	v_sub_f32_e32 v5, v3, v5
	v_sub_f32_e32 v3, v3, v7
	v_add_f32_e32 v5, v2, v5
	v_add_f32_e32 v2, v2, v3
	v_add_f32_e32 v11, v6, v2
	v_rcp_f32_e32 v13, v11
	v_sub_f32_e32 v3, v11, v6
	v_sub_f32_e32 v12, v2, v3
	v_add_f32_e32 v3, v4, v5
	v_mul_f32_e32 v15, v3, v13
	v_sub_f32_e32 v2, v3, v4
	v_mul_f32_e32 v4, v11, v15
	v_fma_f32 v6, v15, v11, -v4
	v_fmac_f32_e32 v6, v15, v12
	v_sub_f32_e32 v14, v5, v2
	v_add_f32_e32 v2, v4, v6
	v_sub_f32_e32 v5, v3, v2
	v_pk_add_f32 v[8:9], v[2:3], v[4:5] neg_lo:[0,1] neg_hi:[0,1]
	v_mov_b32_e32 v7, v2
	v_pk_add_f32 v[2:3], v[8:9], v[6:7] neg_lo:[0,1] neg_hi:[0,1]
	s_mov_b32 s55, 0x3f317218
	v_add_f32_e32 v3, v14, v3
	v_add_f32_e32 v2, v2, v3
	v_add_f32_e32 v3, v5, v2
	v_mul_f32_e32 v14, v13, v3
	v_mul_f32_e32 v4, v11, v14
	v_fma_f32 v6, v14, v11, -v4
	v_fmac_f32_e32 v6, v14, v12
	v_sub_f32_e32 v5, v5, v3
	v_add_f32_e32 v11, v2, v5
	v_add_f32_e32 v2, v4, v6
	v_sub_f32_e32 v5, v3, v2
	v_pk_add_f32 v[8:9], v[2:3], v[4:5] neg_lo:[0,1] neg_hi:[0,1]
	v_mov_b32_e32 v7, v2
	v_pk_add_f32 v[2:3], v[8:9], v[6:7] neg_lo:[0,1] neg_hi:[0,1]
	v_cmp_nlt_f32_e32 vcc, 1.0, v18
	v_add_f32_e32 v3, v11, v3
	v_add_f32_e32 v2, v2, v3
	v_add_f32_e32 v3, v15, v14
	v_add_f32_e32 v2, v5, v2
	v_sub_f32_e32 v4, v3, v15
	v_mul_f32_e32 v2, v13, v2
	v_sub_f32_e32 v4, v14, v4
	v_add_f32_e32 v4, v4, v2
	v_add_f32_e32 v6, v3, v4
	v_mul_f32_e32 v7, v6, v6
	v_fmamk_f32 v2, v7, 0x3e9b6dac, v129
	v_fmaak_f32 v97, v7, v2, 0x3f2aaada
	v_cvt_f32_i32_e32 v2, v10
	v_sub_f32_e32 v3, v6, v3
	v_sub_f32_e32 v3, v4, v3
	v_ldexp_f32 v8, v3, 1
	v_mul_f32_e32 v3, v6, v7
	v_ldexp_f32 v5, v6, 1
	v_pk_mul_f32 v[6:7], v[2:3], v[96:97]
	v_lshl_or_b32 v134, s43, 10, v22
	v_fma_f32 v4, v2, s55, -v6
	v_fmac_f32_e32 v4, 0xb102e308, v2
	v_pk_add_f32 v[2:3], v[6:7], v[4:5]
	s_mov_b32 s55, 0x33800000
	v_sub_f32_e32 v5, v3, v5
	v_sub_f32_e32 v5, v7, v5
	v_add_f32_e32 v9, v8, v5
	v_mov_b32_e32 v8, v6
	v_pk_add_f32 v[6:7], v[2:3], v[6:7] neg_lo:[0,1] neg_hi:[0,1]
	v_pk_add_f32 v[10:11], v[2:3], v[8:9]
	v_mov_b32_e32 v5, v2
	v_mov_b32_e32 v7, v11
	v_pk_add_f32 v[12:13], v[4:5], v[6:7] neg_lo:[0,1] neg_hi:[0,1]
	v_pk_add_f32 v[4:5], v[4:5], v[6:7]
	v_mov_b32_e32 v16, v3
	v_pk_add_f32 v[6:7], v[4:5], v[2:3] op_sel:[1,0] op_sel_hi:[0,1] neg_lo:[0,1] neg_hi:[0,1]
	v_pk_add_f32 v[14:15], v[10:11], v[6:7] op_sel_hi:[1,0] neg_lo:[0,1] neg_hi:[0,1]
	v_mov_b32_e32 v10, v11
	v_mov_b32_e32 v11, v5
	v_mov_b32_e32 v17, v6
	v_pk_add_f32 v[6:7], v[10:11], v[16:17] neg_lo:[0,1] neg_hi:[0,1]
	v_mov_b32_e32 v8, v9
	v_mov_b32_e32 v9, v2
	v_pk_add_f32 v[2:3], v[8:9], v[6:7] neg_lo:[0,1] neg_hi:[0,1]
	v_mov_b32_e32 v14, v12
	v_pk_add_f32 v[6:7], v[14:15], v[2:3]
	v_mov_b32_e32 v13, v5
	v_pk_add_f32 v[8:9], v[6:7], v[6:7] op_sel:[0,1] op_sel_hi:[1,0]
	s_movk_i32 s43, 0x2000
	v_pk_add_f32 v[4:5], v[4:5], v[8:9] op_sel:[1,0] op_sel_hi:[0,1]
	v_mov_b32_e32 v7, v4
	v_pk_add_f32 v[10:11], v[6:7], v[12:13] neg_lo:[0,1] neg_hi:[0,1]
	v_mov_b32_e32 v3, v8
	v_sub_f32_e32 v5, v6, v10
	v_pk_add_f32 v[2:3], v[2:3], v[10:11] neg_lo:[0,1] neg_hi:[0,1]
	v_sub_f32_e32 v5, v12, v5
	v_add_f32_e32 v2, v2, v5
	v_add_f32_e32 v2, v2, v3
	v_add_f32_e32 v2, v4, v2
	v_cndmask_b32_e32 v2, v131, v2, vcc
	v_cmp_neq_f32_e32 vcc, 1.0, v18
	s_nop 1
	v_cndmask_b32_e32 v2, v132, v2, vcc
	v_cmp_gt_f32_e32 vcc, s55, v18
	s_mul_hi_i32 s55, s58, 0x22000
	s_addc_u32 s73, s61, s55
	s_lshl_b32 s66, s54, 9
	v_cndmask_b32_e64 v97, v2, -v18, vcc
	v_lshl_add_u64 v[100:101], v[52:53], 0, s[66:67]
	v_add_u32_e32 v2, s42, v105
	v_mad_i64_i32 v[10:11], s[54:55], v2, s3, v[100:101]
	global_load_dwordx4 v[6:9], v[10:11], off nt
	global_load_dwordx4 v[2:5], v[10:11], off offset:256 nt
	global_load_dwordx4 v[14:17], v[10:11], off offset:2048 nt
	s_nop 0
	global_load_dwordx4 v[10:13], v[10:11], off offset:2304 nt
	s_nop 0
	global_load_dwordx4 v[18:21], v[54:55], off offset:48
	global_load_dwordx4 v[26:29], v[54:55], off offset:32
	global_load_dwordx4 v[34:37], v[54:55], off offset:16
	global_load_dwordx4 v[42:45], v[54:55], off
	global_load_dwordx4 v[22:25], v134, s[62:63] offset:48
	global_load_dwordx4 v[30:33], v134, s[62:63] offset:32
	global_load_dwordx4 v[38:41], v134, s[62:63] offset:16
	global_load_dwordx4 v[46:49], v134, s[62:63]
	v_lshl_add_u64 v[98:99], s[72:73], 0, v[50:51]
	s_waitcnt vmcnt(0)
; DI unsigned pk_bf16(float a, float b) { f32x2 v = {a, b}; bf2_t r = __builtin_convertvector(v, bf2_t); return __builtin_bit_cast(unsigned, r); }
; DI float bflo(unsigned u) { return __uint_as_float(u << 16); }
; DI float bfhi(unsigned u) { return __uint_as_float(u & 0xffff0000u); }
; DI void phase_ret_prep(const Params& p, unsigned char* smem) {
;     ...
;             for (int j = 0; j < 8; ++j) {
;                 const f32x2 tr = tabR[row * 128 + i0 + j], tc = tabC[n * 128 + i0 + j];
;                 const float cs = tc.x * tr.x - tc.y * tr.y, sn = tc.y * tr.x + tc.x * tr.y;
;                 const float x1 = (j & 1) ? bfhi(q1u[j >> 1]) : bflo(q1u[j >> 1]), x2 = (j & 1) ? bfhi(q2u[j >> 1]) : bflo(q2u[j >> 1]);
;                 const float y1 = (j & 1) ? bfhi(k1u[j >> 1]) : bflo(k1u[j >> 1]), y2 = (j & 1) ? bfhi(k2u[j >> 1]) : bflo(k2u[j >> 1]);
;                 qa[j] = x1 * cs - x2 * sn; qb[j] = x1 * sn + x2 * cs;
;                 ka[j] = (y1 * cs - y2 * sn) * 0.0625f; kb[j] = (y1 * sn + y2 * cs) * 0.0625f;
;             }
;             const float qdec = expf(lg * (float)(row + 1));
;             u32x4 w;
;             w.x = pk_bf16(qa[0], qa[1]); w.y = pk_bf16(qa[2], qa[3]); w.z = pk_bf16(qa[4], qa[5]); w.w = pk_bf16(qa[6], qa[7]); *(u32x4*)(qr + row * 264 + i0) = w;
;             w.x = pk_bf16(qb[0], qb[1]); w.y = pk_bf16(qb[2], qb[3]); w.z = pk_bf16(qb[4], qb[5]); w.w = pk_bf16(qb[6], qb[7]); *(u32x4*)(qr + row * 264 + 128 + i0) = w;
;             w.x = pk_bf16(ka[0], ka[1]); w.y = pk_bf16(ka[2], ka[3]); w.z = pk_bf16(ka[4], ka[5]); w.w = pk_bf16(ka[6], ka[7]); *(u32x4*)(kr + row * 264 + i0) = w;
;             w.x = pk_bf16(kb[0], kb[1]); w.y = pk_bf16(kb[2], kb[3]); w.z = pk_bf16(kb[4], kb[5]); w.w = pk_bf16(kb[6], kb[7]); *(u32x4*)(kr + row * 264 + 128 + i0) = w;
	v_lshlrev_b32_e32 v142, 16, v2
	v_and_b32_e32 v143, 0xffff0000, v2
	v_mov_b32_e32 v137, v44
	v_mov_b32_e32 v139, v48
	v_mov_b32_e32 v44, v43
	v_mov_b32_e32 v48, v47
	v_mov_b32_e32 v136, v42
	v_mov_b32_e32 v138, v46
	v_pk_mul_f32 v[42:43], v[44:45], v[48:49]
	s_nop 0
	v_pk_fma_f32 v[140:141], v[136:137], v[138:139], v[42:43] neg_lo:[0,0,1] neg_hi:[0,0,1]
	v_pk_mul_f32 v[42:43], v[44:45], v[138:139]
	v_lshlrev_b32_e32 v138, 16, v10
	v_and_b32_e32 v139, 0xffff0000, v10
	v_pk_fma_f32 v[48:49], v[136:137], v[48:49], v[42:43]
	v_lshlrev_b32_e32 v136, 16, v14
	v_and_b32_e32 v137, 0xffff0000, v14
	v_pk_mul_f32 v[42:43], v[140:141], v[138:139]
	v_lshlrev_b32_e32 v44, 16, v6
	v_pk_fma_f32 v[42:43], v[48:49], v[136:137], v[42:43]
	v_and_b32_e32 v45, 0xffff0000, v6
	v_pk_mul_f32 v[46:47], v[42:43], s[70:71] op_sel_hi:[1,0]
	v_pk_mul_f32 v[42:43], v[140:141], v[142:143]
	v_pk_mul_f32 v[142:143], v[48:49], v[142:143]
	v_pk_fma_f32 v[42:43], v[48:49], v[44:45], v[42:43]
	v_pk_mul_f32 v[48:49], v[48:49], v[138:139]
	v_mov_b32_e32 v138, v38
	v_pk_fma_f32 v[48:49], v[140:141], v[136:137], v[48:49] neg_lo:[0,0,1] neg_hi:[0,0,1]
	v_mov_b32_e32 v137, v36
	v_mov_b32_e32 v139, v40
	v_mov_b32_e32 v36, v35
	v_mov_b32_e32 v40, v39
	v_mov_b32_e32 v136, v34
	v_pk_mul_f32 v[34:35], v[36:37], v[40:41]
	v_pk_mul_f32 v[36:37], v[36:37], v[138:139]
	v_pk_fma_f32 v[34:35], v[136:137], v[138:139], v[34:35] neg_lo:[0,0,1] neg_hi:[0,0,1]
	v_pk_fma_f32 v[36:37], v[136:137], v[40:41], v[36:37]
	v_lshlrev_b32_e32 v38, 16, v11
	v_and_b32_e32 v39, 0xffff0000, v11
	v_lshlrev_b32_e32 v40, 16, v3
	v_and_b32_e32 v41, 0xffff0000, v3
	v_lshlrev_b32_e32 v14, 16, v15
	v_and_b32_e32 v15, 0xffff0000, v15
	v_pk_mul_f32 v[10:11], v[34:35], v[38:39]
	v_lshlrev_b32_e32 v6, 16, v7
	v_and_b32_e32 v7, 0xffff0000, v7
	v_pk_mul_f32 v[2:3], v[34:35], v[40:41]
	v_pk_fma_f32 v[10:11], v[36:37], v[14:15], v[10:11]
	v_pk_fma_f32 v[2:3], v[36:37], v[6:7], v[2:3]
	v_pk_mul_f32 v[40:41], v[36:37], v[40:41]
	v_pk_mul_f32 v[36:37], v[36:37], v[38:39]
	v_pk_fma_f32 v[6:7], v[34:35], v[6:7], v[40:41] neg_lo:[0,0,1] neg_hi:[0,0,1]
	v_pk_fma_f32 v[14:15], v[34:35], v[14:15], v[36:37] neg_lo:[0,0,1] neg_hi:[0,0,1]
	v_mov_b32_e32 v37, v32
	v_pk_mul_f32 v[34:35], v[14:15], s[70:71] op_sel_hi:[1,0]
	v_mov_b32_e32 v15, v28
	v_mov_b32_e32 v28, v27
	v_mov_b32_e32 v32, v31
	v_mov_b32_e32 v14, v26
	v_mov_b32_e32 v36, v30
	v_pk_mul_f32 v[26:27], v[28:29], v[32:33]
	v_lshlrev_b32_e32 v40, 16, v4
	v_pk_fma_f32 v[30:31], v[14:15], v[36:37], v[26:27] neg_lo:[0,0,1] neg_hi:[0,0,1]
	v_pk_mul_f32 v[26:27], v[28:29], v[36:37]
	v_lshlrev_b32_e32 v36, 16, v12
	v_and_b32_e32 v37, 0xffff0000, v12
	v_pk_fma_f32 v[28:29], v[14:15], v[32:33], v[26:27]
	v_lshlrev_b32_e32 v32, 16, v16
	v_and_b32_e32 v33, 0xffff0000, v16
	v_pk_mul_f32 v[14:15], v[30:31], v[36:37]
	v_and_b32_e32 v41, 0xffff0000, v4
	v_pk_fma_f32 v[14:15], v[28:29], v[32:33], v[14:15]
	v_lshlrev_b32_e32 v26, 16, v8
	v_pk_mul_f32 v[38:39], v[14:15], s[70:71] op_sel_hi:[1,0]
	v_and_b32_e32 v27, 0xffff0000, v8
	v_pk_mul_f32 v[14:15], v[30:31], v[40:41]
	v_pk_mul_f32 v[40:41], v[28:29], v[40:41]
	v_pk_fma_f32 v[14:15], v[28:29], v[26:27], v[14:15]
	v_pk_mul_f32 v[28:29], v[28:29], v[36:37]
	v_pk_fma_f32 v[26:27], v[30:31], v[26:27], v[40:41] neg_lo:[0,0,1] neg_hi:[0,0,1]
	v_pk_fma_f32 v[28:29], v[30:31], v[32:33], v[28:29] neg_lo:[0,0,1] neg_hi:[0,0,1]
	v_mov_b32_e32 v31, v20
	v_mov_b32_e32 v32, v22
	v_mov_b32_e32 v33, v24
	v_mov_b32_e32 v20, v19
	v_mov_b32_e32 v24, v23
	v_mov_b32_e32 v30, v18
	v_pk_mul_f32 v[18:19], v[20:21], v[24:25]
	v_pk_mul_f32 v[20:21], v[20:21], v[32:33]
	v_pk_fma_f32 v[18:19], v[30:31], v[32:33], v[18:19] neg_lo:[0,0,1] neg_hi:[0,0,1]
	v_pk_fma_f32 v[20:21], v[30:31], v[24:25], v[20:21]
	v_lshlrev_b32_e32 v4, 16, v5
	v_and_b32_e32 v5, 0xffff0000, v5
	v_lshlrev_b32_e32 v12, 16, v13
	v_and_b32_e32 v13, 0xffff0000, v13
	v_lshlrev_b32_e32 v8, 16, v9
	v_and_b32_e32 v9, 0xffff0000, v9
	v_pk_mul_f32 v[24:25], v[18:19], v[4:5]
	v_pk_mul_f32 v[4:5], v[20:21], v[4:5]
	v_pk_mul_f32 v[22:23], v[18:19], v[12:13]
	v_pk_fma_f32 v[24:25], v[20:21], v[8:9], v[24:25]
	v_pk_fma_f32 v[4:5], v[18:19], v[8:9], v[4:5] neg_lo:[0,0,1] neg_hi:[0,0,1]
	v_pk_mul_f32 v[8:9], v[20:21], v[12:13]
	v_mul_f32_e32 v12, v97, v106
	v_lshlrev_b32_e32 v16, 16, v17
	v_and_b32_e32 v17, 0xffff0000, v17
	v_mul_f32_e32 v13, 0x3fb8aa3b, v12
	v_pk_fma_f32 v[22:23], v[20:21], v[16:17], v[22:23]
	v_pk_fma_f32 v[8:9], v[18:19], v[16:17], v[8:9] neg_lo:[0,0,1] neg_hi:[0,0,1]
	v_fma_f32 v16, v12, s33, -v13
	v_rndne_f32_e32 v17, v13
	v_fmac_f32_e32 v16, 0x32a5705f, v12
	v_sub_f32_e32 v13, v13, v17
	v_add_f32_e32 v13, v13, v16
	v_exp_f32_e32 v13, v13
	v_cvt_i32_f32_e32 v16, v17
	v_pk_fma_f32 v[44:45], v[140:141], v[44:45], v[142:143] neg_lo:[0,0,1] neg_hi:[0,0,1]
	v_cmp_ngt_f32_e32 vcc, s47, v12
	v_cvt_pk_bf16_f32 v17, v6, v7
	v_ldexp_f32 v13, v13, v16
	v_cvt_pk_bf16_f32 v16, v44, v45
	v_cvt_pk_bf16_f32 v18, v26, v27
	v_cvt_pk_bf16_f32 v19, v4, v5
	v_pk_mul_f32 v[10:11], v[10:11], s[70:71] op_sel_hi:[1,0]
	v_pk_mul_f32 v[22:23], v[22:23], s[70:71] op_sel_hi:[1,0]
	v_pk_mul_f32 v[8:9], v[8:9], s[70:71] op_sel_hi:[1,0]
	v_cndmask_b32_e32 v13, 0, v13, vcc
	v_cmp_nlt_f32_e32 vcc, s53, v12
	ds_write_b128 v107, v[16:19]
	v_cvt_pk_bf16_f32 v16, v42, v43
	v_cvt_pk_bf16_f32 v17, v2, v3
	v_cvt_pk_bf16_f32 v18, v14, v15
	v_cvt_pk_bf16_f32 v19, v24, v25
	v_cndmask_b32_e32 v12, v133, v13, vcc
	ds_write_b128 v107, v[16:19] offset:256
	v_cvt_pk_bf16_f32 v19, v8, v9
	v_cvt_pk_bf16_f32 v8, v46, v47
	v_cvt_pk_bf16_f32 v9, v10, v11
	v_cvt_pk_bf16_f32 v10, v38, v39
	v_cvt_pk_bf16_f32 v11, v22, v23
	ds_write_b128 v107, v[8:11] offset:34048
; DI unsigned pk_bf16(float a, float b) { f32x2 v = {a, b}; bf2_t r = __builtin_convertvector(v, bf2_t); return __builtin_bit_cast(unsigned, r); }
; DI float bflo(unsigned u) { return __uint_as_float(u << 16); }
; DI float bfhi(unsigned u) { return __uint_as_float(u & 0xffff0000u); }
; DI void phase_ret_prep(const Params& p, unsigned char* smem) {
;     ...
;         for (int m = 0; m < 2; ++m) {
;             const int e = tid + 512 * m, row = e >> 4, i0 = (e & 15) * 8;
;             const bf16_t* src = P1 + (size_t)(tok0 + row) * LDP1 + h * 256 + i0;
;             const u32x4 q1 = *(const u32x4*)src, q2 = *(const u32x4*)(src + 128), k1 = *(const u32x4*)(src + 1024), k2 = *(const u32x4*)(src + 1152);
;             const unsigned q1u[4] = {q1.x, q1.y, q1.z, q1.w}, q2u[4] = {q2.x, q2.y, q2.z, q2.w}, k1u[4] = {k1.x, k1.y, k1.z, k1.w}, k2u[4] = {k2.x, k2.y, k2.z, k2.w};
;             float qa[8], qb[8], ka[8], kb[8];
; #pragma unroll
;             for (int j = 0; j < 8; ++j) {
;                 const f32x2 tr = tabR[row * 128 + i0 + j], tc = tabC[n * 128 + i0 + j];
;                 const float cs = tc.x * tr.x - tc.y * tr.y, sn = tc.y * tr.x + tc.x * tr.y;
;                 const float x1 = (j & 1) ? bfhi(q1u[j >> 1]) : bflo(q1u[j >> 1]), x2 = (j & 1) ? bfhi(q2u[j >> 1]) : bflo(q2u[j >> 1]);
;                 const float y1 = (j & 1) ? bfhi(k1u[j >> 1]) : bflo(k1u[j >> 1]), y2 = (j & 1) ? bfhi(k2u[j >> 1]) : bflo(k2u[j >> 1]);
;                 qa[j] = x1 * cs - x2 * sn; qb[j] = x1 * sn + x2 * cs;
;                 ka[j] = (y1 * cs - y2 * sn) * 0.0625f; kb[j] = (y1 * sn + y2 * cs) * 0.0625f;
;     ...
;             { u32x2 w0, w1; bf16_t* fp = o_qd + ((((row >> 5) * 16 + (i0 >> 4)) * 64 + (row & 31)) << 3) + ((i0 >> 3) & 1) * 4;
;               w0.x = pk_bf16(qa[0] * qdec, qa[1] * qdec); w0.y = pk_bf16(qa[2] * qdec, qa[3] * qdec); w1.x = pk_bf16(qa[4] * qdec, qa[5] * qdec); w1.y = pk_bf16(qa[6] * qdec, qa[7] * qdec);
;               *(u32x2*)fp = w0; *(u32x2*)(fp + 32 * 8) = w1;
;               w0.x = pk_bf16(qb[0] * qdec, qb[1] * qdec); w0.y = pk_bf16(qb[2] * qdec, qb[3] * qdec); w1.x = pk_bf16(qb[4] * qdec, qb[5] * qdec); w1.y = pk_bf16(qb[6] * qdec, qb[7] * qdec);
;               *(u32x2*)(fp + 8 * 64 * 8) = w0; *(u32x2*)(fp + 8 * 64 * 8 + 32 * 8) = w1; }
	v_pk_mul_f32 v[10:11], v[44:45], v[12:13] op_sel_hi:[1,0]
	v_pk_mul_f32 v[6:7], v[6:7], v[12:13] op_sel_hi:[1,0]
	v_pk_mul_f32 v[48:49], v[48:49], s[70:71] op_sel_hi:[1,0]
	v_pk_mul_f32 v[28:29], v[28:29], s[70:71] op_sel_hi:[1,0]
	v_cvt_pk_bf16_f32 v10, v10, v11
	v_cvt_pk_bf16_f32 v11, v6, v7
	v_pk_mul_f32 v[6:7], v[26:27], v[12:13] op_sel_hi:[1,0]
	v_pk_mul_f32 v[4:5], v[4:5], v[12:13] op_sel_hi:[1,0]
	v_cvt_pk_bf16_f32 v16, v48, v49
	v_cvt_pk_bf16_f32 v17, v34, v35
	v_cvt_pk_bf16_f32 v18, v28, v29
	v_lshl_add_u64 v[8:9], v[56:57], 1, v[98:99]
	v_cvt_pk_bf16_f32 v6, v6, v7
	v_cvt_pk_bf16_f32 v7, v4, v5
	v_pk_mul_f32 v[4:5], v[42:43], v[12:13] op_sel_hi:[1,0]
	v_pk_mul_f32 v[2:3], v[2:3], v[12:13] op_sel_hi:[1,0]
	ds_write_b128 v107, v[16:19] offset:33792
	global_store_dwordx2 v[8:9], v[10:11], off
	global_store_dwordx2 v[8:9], v[6:7], off offset:512
	v_cvt_pk_bf16_f32 v4, v4, v5
	v_cvt_pk_bf16_f32 v5, v2, v3
	v_pk_mul_f32 v[2:3], v[14:15], v[12:13] op_sel_hi:[1,0]
	v_pk_mul_f32 v[6:7], v[24:25], v[12:13] op_sel_hi:[1,0]
	v_cvt_pk_bf16_f32 v2, v2, v3
	v_cvt_pk_bf16_f32 v3, v6, v7
	v_add_co_u32_e32 v6, vcc, s43, v8
	s_nop 1
	v_addc_co_u32_e32 v7, vcc, 0, v9, vcc
	global_store_dwordx2 v[6:7], v[4:5], off
	global_store_dwordx2 v[6:7], v[2:3], off offset:512
	v_add_u32_e32 v2, s42, v108
	v_mad_i64_i32 v[10:11], s[42:43], v2, s3, v[100:101]
	global_load_dwordx4 v[6:9], v[10:11], off nt
	global_load_dwordx4 v[2:5], v[10:11], off offset:256 nt
	global_load_dwordx4 v[14:17], v[10:11], off offset:2048 nt
	s_nop 0
	global_load_dwordx4 v[10:13], v[10:11], off offset:2304 nt
	s_nop 0
	global_load_dwordx4 v[18:21], v[58:59], off offset:48
	global_load_dwordx4 v[26:29], v[58:59], off offset:32
	global_load_dwordx4 v[34:37], v[58:59], off offset:16
	global_load_dwordx4 v[42:45], v[58:59], off
	global_load_dwordx4 v[22:25], v134, s[62:63] offset:48
	global_load_dwordx4 v[30:33], v134, s[62:63] offset:32
	global_load_dwordx4 v[38:41], v134, s[62:63] offset:16
	global_load_dwordx4 v[46:49], v134, s[62:63]
	s_waitcnt vmcnt(0)
	v_lshlrev_b32_e32 v136, 16, v2
	v_and_b32_e32 v137, 0xffff0000, v2
	v_lshlrev_b32_e32 v2, 16, v3
	v_and_b32_e32 v3, 0xffff0000, v3
	v_mov_b32_e32 v101, v44
	v_mov_b32_e32 v44, v43
	v_mov_b32_e32 v100, v42
	v_mov_b32_e32 v134, v46
	v_mov_b32_e32 v135, v48
	v_mov_b32_e32 v48, v47
	v_pk_mul_f32 v[42:43], v[44:45], v[48:49]
	v_pk_mul_f32 v[44:45], v[44:45], v[134:135]
	v_pk_fma_f32 v[42:43], v[100:101], v[134:135], v[42:43] neg_lo:[0,0,1] neg_hi:[0,0,1]
	v_pk_fma_f32 v[44:45], v[100:101], v[48:49], v[44:45]
	v_lshlrev_b32_e32 v48, 16, v10
	v_and_b32_e32 v49, 0xffff0000, v10
	v_lshlrev_b32_e32 v46, 16, v14
	v_and_b32_e32 v47, 0xffff0000, v14
	v_pk_mul_f32 v[100:101], v[42:43], v[48:49]
	v_lshlrev_b32_e32 v134, 16, v6
	v_and_b32_e32 v135, 0xffff0000, v6
	v_pk_mul_f32 v[138:139], v[42:43], v[136:137]
	v_pk_fma_f32 v[100:101], v[44:45], v[46:47], v[100:101]
	v_pk_fma_f32 v[138:139], v[44:45], v[134:135], v[138:139]
	v_pk_mul_f32 v[136:137], v[44:45], v[136:137]
	v_pk_mul_f32 v[44:45], v[44:45], v[48:49]
	v_pk_fma_f32 v[134:135], v[42:43], v[134:135], v[136:137] neg_lo:[0,0,1] neg_hi:[0,0,1]
	v_pk_fma_f32 v[42:43], v[42:43], v[46:47], v[44:45] neg_lo:[0,0,1] neg_hi:[0,0,1]
	v_mov_b32_e32 v45, v36
	v_mov_b32_e32 v46, v38
	v_mov_b32_e32 v47, v40
	v_mov_b32_e32 v36, v35
	v_mov_b32_e32 v40, v39
	v_mov_b32_e32 v44, v34
	v_pk_mul_f32 v[34:35], v[36:37], v[40:41]
	v_pk_mul_f32 v[36:37], v[36:37], v[46:47]
	v_pk_fma_f32 v[34:35], v[44:45], v[46:47], v[34:35] neg_lo:[0,0,1] neg_hi:[0,0,1]
	v_pk_fma_f32 v[36:37], v[44:45], v[40:41], v[36:37]
	v_lshlrev_b32_e32 v10, 16, v11
	v_and_b32_e32 v11, 0xffff0000, v11
	v_lshlrev_b32_e32 v6, 16, v7
	v_and_b32_e32 v7, 0xffff0000, v7
	v_pk_mul_f32 v[40:41], v[34:35], v[2:3]
	v_pk_mul_f32 v[2:3], v[36:37], v[2:3]
	v_lshlrev_b32_e32 v14, 16, v15
	v_and_b32_e32 v15, 0xffff0000, v15
	v_pk_fma_f32 v[40:41], v[36:37], v[6:7], v[40:41]
	v_pk_fma_f32 v[6:7], v[34:35], v[6:7], v[2:3] neg_lo:[0,0,1] neg_hi:[0,0,1]
	v_pk_mul_f32 v[2:3], v[36:37], v[10:11]
	v_pk_mul_f32 v[38:39], v[34:35], v[10:11]
	v_pk_fma_f32 v[2:3], v[34:35], v[14:15], v[2:3] neg_lo:[0,0,1] neg_hi:[0,0,1]
	v_pk_fma_f32 v[38:39], v[36:37], v[14:15], v[38:39]
	v_pk_mul_f32 v[10:11], v[2:3], s[70:71] op_sel_hi:[1,0]
	v_mov_b32_e32 v3, v28
	v_mov_b32_e32 v15, v32
	v_mov_b32_e32 v28, v27
	v_mov_b32_e32 v32, v31
	v_mov_b32_e32 v2, v26
	v_mov_b32_e32 v14, v30
	v_pk_mul_f32 v[26:27], v[28:29], v[32:33]
	v_lshlrev_b32_e32 v34, 16, v4
	v_pk_fma_f32 v[26:27], v[2:3], v[14:15], v[26:27] neg_lo:[0,0,1] neg_hi:[0,0,1]
	v_pk_mul_f32 v[14:15], v[28:29], v[14:15]
	v_lshlrev_b32_e32 v28, 16, v12
	v_and_b32_e32 v29, 0xffff0000, v12
	v_and_b32_e32 v35, 0xffff0000, v4
	v_pk_fma_f32 v[2:3], v[2:3], v[32:33], v[14:15]
	v_lshlrev_b32_e32 v14, 16, v16
	v_and_b32_e32 v15, 0xffff0000, v16
	v_pk_mul_f32 v[30:31], v[26:27], v[28:29]
	v_lshlrev_b32_e32 v32, 16, v8
	v_and_b32_e32 v33, 0xffff0000, v8
	v_pk_mul_f32 v[36:37], v[26:27], v[34:35]
	v_pk_fma_f32 v[30:31], v[2:3], v[14:15], v[30:31]
	v_pk_fma_f32 v[36:37], v[2:3], v[32:33], v[36:37]
	v_pk_mul_f32 v[34:35], v[2:3], v[34:35]
	v_pk_mul_f32 v[2:3], v[2:3], v[28:29]
	v_pk_fma_f32 v[32:33], v[26:27], v[32:33], v[34:35] neg_lo:[0,0,1] neg_hi:[0,0,1]
	v_pk_fma_f32 v[2:3], v[26:27], v[14:15], v[2:3] neg_lo:[0,0,1] neg_hi:[0,0,1]
	v_mov_b32_e32 v27, v24
	v_pk_mul_f32 v[14:15], v[2:3], s[70:71] op_sel_hi:[1,0]
	v_mov_b32_e32 v3, v20
	v_mov_b32_e32 v20, v19
	v_mov_b32_e32 v24, v23
	v_mov_b32_e32 v2, v18
	v_mov_b32_e32 v26, v22
	v_pk_mul_f32 v[18:19], v[20:21], v[24:25]
	v_pk_mul_f32 v[20:21], v[20:21], v[26:27]
; DI unsigned pk_bf16(float a, float b) { f32x2 v = {a, b}; bf2_t r = __builtin_convertvector(v, bf2_t); return __builtin_bit_cast(unsigned, r); }
; DI float bf2f(bf16_t b) { return __uint_as_float(((unsigned)b) << 16); }
; DI void phase_ret_prep(const Params& p, unsigned char* smem) {
;     ...
;             const float qdec = expf(lg * (float)(row + 1));
;             u32x4 w;
;             w.x = pk_bf16(qa[0], qa[1]); w.y = pk_bf16(qa[2], qa[3]); w.z = pk_bf16(qa[4], qa[5]); w.w = pk_bf16(qa[6], qa[7]); *(u32x4*)(qr + row * 264 + i0) = w;
;             w.x = pk_bf16(qb[0], qb[1]); w.y = pk_bf16(qb[2], qb[3]); w.z = pk_bf16(qb[4], qb[5]); w.w = pk_bf16(qb[6], qb[7]); *(u32x4*)(qr + row * 264 + 128 + i0) = w;
;             w.x = pk_bf16(ka[0], ka[1]); w.y = pk_bf16(ka[2], ka[3]); w.z = pk_bf16(ka[4], ka[5]); w.w = pk_bf16(ka[6], ka[7]); *(u32x4*)(kr + row * 264 + i0) = w;
;             w.x = pk_bf16(kb[0], kb[1]); w.y = pk_bf16(kb[2], kb[3]); w.z = pk_bf16(kb[4], kb[5]); w.w = pk_bf16(kb[6], kb[7]); *(u32x4*)(kr + row * 264 + 128 + i0) = w;
;             { u32x2 w0, w1; bf16_t* fp = o_qd + ((((row >> 5) * 16 + (i0 >> 4)) * 64 + (row & 31)) << 3) + ((i0 >> 3) & 1) * 4;
;               w0.x = pk_bf16(qa[0] * qdec, qa[1] * qdec); w0.y = pk_bf16(qa[2] * qdec, qa[3] * qdec); w1.x = pk_bf16(qa[4] * qdec, qa[5] * qdec); w1.y = pk_bf16(qa[6] * qdec, qa[7] * qdec);
;               *(u32x2*)fp = w0; *(u32x2*)(fp + 32 * 8) = w1;
;               w0.x = pk_bf16(qb[0] * qdec, qb[1] * qdec); w0.y = pk_bf16(qb[2] * qdec, qb[3] * qdec); w1.x = pk_bf16(qb[4] * qdec, qb[5] * qdec); w1.y = pk_bf16(qb[6] * qdec, qb[7] * qdec);
;               *(u32x2*)(fp + 8 * 64 * 8) = w0; *(u32x2*)(fp + 8 * 64 * 8 + 32 * 8) = w1; }
;         }
;         lds_barrier();
;     ...
;         } else {
;             const int dk = tid - 256;
; #pragma unroll
;             for (int i0 = 0; i0 < 64; i0 += 8) { float v[8];
; #pragma unroll
;                 for (int j = 0; j < 8; ++j) v[j] = bf2f(kr[(i0 + j) * 264 + dk]) * __expf(lg * (float)(63 - i0 - j));
;                 u32x4 w; w.x = pk_bf16(v[0], v[1]); w.y = pk_bf16(v[2], v[3]); w.z = pk_bf16(v[4], v[5]); w.w = pk_bf16(v[6], v[7]);
;                 *(u32x4*)(o_kdT + ((((dk >> 5) * 4 + (i0 >> 4)) * 64 + (dk & 31) + 32 * ((i0 >> 3) & 1)) << 3)) = w; }
	v_pk_fma_f32 v[18:19], v[2:3], v[26:27], v[18:19] neg_lo:[0,0,1] neg_hi:[0,0,1]
	v_lshlrev_b32_e32 v12, 16, v13
	v_and_b32_e32 v13, 0xffff0000, v13
	v_lshlrev_b32_e32 v4, 16, v5
	v_and_b32_e32 v5, 0xffff0000, v5
	v_pk_fma_f32 v[2:3], v[2:3], v[24:25], v[20:21]
	v_lshlrev_b32_e32 v16, 16, v17
	v_and_b32_e32 v17, 0xffff0000, v17
	v_pk_mul_f32 v[20:21], v[18:19], v[12:13]
	v_lshlrev_b32_e32 v8, 16, v9
	v_and_b32_e32 v9, 0xffff0000, v9
	v_pk_mul_f32 v[22:23], v[18:19], v[4:5]
	v_pk_fma_f32 v[20:21], v[2:3], v[16:17], v[20:21]
	v_pk_fma_f32 v[22:23], v[2:3], v[8:9], v[22:23]
	v_pk_mul_f32 v[4:5], v[2:3], v[4:5]
	v_pk_mul_f32 v[2:3], v[2:3], v[12:13]
	v_pk_fma_f32 v[8:9], v[18:19], v[8:9], v[4:5] neg_lo:[0,0,1] neg_hi:[0,0,1]
	v_pk_fma_f32 v[2:3], v[18:19], v[16:17], v[2:3] neg_lo:[0,0,1] neg_hi:[0,0,1]
	v_pk_mul_f32 v[42:43], v[42:43], s[70:71] op_sel_hi:[1,0]
	v_pk_mul_f32 v[12:13], v[2:3], s[70:71] op_sel_hi:[1,0]
	v_mul_f32_e32 v2, v97, v109
	v_mul_f32_e32 v3, 0x3fb8aa3b, v2
	v_fma_f32 v4, v2, s33, -v3
	v_rndne_f32_e32 v5, v3
	v_fmac_f32_e32 v4, 0x32a5705f, v2
	v_sub_f32_e32 v3, v3, v5
	v_add_f32_e32 v3, v3, v4
	v_exp_f32_e32 v3, v3
	v_cvt_i32_f32_e32 v4, v5
	v_cmp_ngt_f32_e32 vcc, s47, v2
	v_cvt_pk_bf16_f32 v5, v8, v9
	v_pk_mul_f32 v[100:101], v[100:101], s[70:71] op_sel_hi:[1,0]
	v_ldexp_f32 v3, v3, v4
	v_cndmask_b32_e32 v3, 0, v3, vcc
	v_cmp_nlt_f32_e32 vcc, s53, v2
	v_cvt_pk_bf16_f32 v2, v134, v135
	v_cvt_pk_bf16_f32 v4, v32, v33
	v_cndmask_b32_e32 v16, v133, v3, vcc
	v_cvt_pk_bf16_f32 v3, v6, v7
	ds_write_b128 v110, v[2:5]
	v_cvt_pk_bf16_f32 v2, v138, v139
	v_cvt_pk_bf16_f32 v3, v40, v41
	v_cvt_pk_bf16_f32 v4, v36, v37
	v_cvt_pk_bf16_f32 v5, v22, v23
	v_pk_mul_f32 v[38:39], v[38:39], s[70:71] op_sel_hi:[1,0]
	v_pk_mul_f32 v[30:31], v[30:31], s[70:71] op_sel_hi:[1,0]
	v_pk_mul_f32 v[20:21], v[20:21], s[70:71] op_sel_hi:[1,0]
	ds_write_b128 v110, v[2:5] offset:256
	v_cvt_pk_bf16_f32 v2, v42, v43
	v_cvt_pk_bf16_f32 v3, v10, v11
	v_cvt_pk_bf16_f32 v4, v14, v15
	v_cvt_pk_bf16_f32 v5, v12, v13
	ds_write_b128 v110, v[2:5] offset:33792
	v_cvt_pk_bf16_f32 v2, v100, v101
	v_cvt_pk_bf16_f32 v3, v38, v39
	v_cvt_pk_bf16_f32 v4, v30, v31
	v_cvt_pk_bf16_f32 v5, v20, v21
	ds_write_b128 v110, v[2:5] offset:34048
	v_pk_mul_f32 v[4:5], v[134:135], v[16:17] op_sel_hi:[1,0]
	v_pk_mul_f32 v[6:7], v[6:7], v[16:17] op_sel_hi:[1,0]
	v_cvt_pk_bf16_f32 v4, v4, v5
	v_cvt_pk_bf16_f32 v5, v6, v7
	v_pk_mul_f32 v[6:7], v[32:33], v[16:17] op_sel_hi:[1,0]
	v_pk_mul_f32 v[8:9], v[8:9], v[16:17] op_sel_hi:[1,0]
	v_lshl_add_u64 v[2:3], v[60:61], 1, v[98:99]
	v_cvt_pk_bf16_f32 v6, v6, v7
	v_cvt_pk_bf16_f32 v7, v8, v9
	global_store_dwordx2 v[2:3], v[4:5], off
	global_store_dwordx2 v[2:3], v[6:7], off offset:512
	v_pk_mul_f32 v[4:5], v[138:139], v[16:17] op_sel_hi:[1,0]
	v_pk_mul_f32 v[6:7], v[40:41], v[16:17] op_sel_hi:[1,0]
	v_add_co_u32_e32 v2, vcc, 0x2000, v2
	v_cvt_pk_bf16_f32 v4, v4, v5
	v_cvt_pk_bf16_f32 v5, v6, v7
	v_pk_mul_f32 v[6:7], v[36:37], v[16:17] op_sel_hi:[1,0]
	v_pk_mul_f32 v[8:9], v[22:23], v[16:17] op_sel_hi:[1,0]
	v_addc_co_u32_e32 v3, vcc, 0, v3, vcc
	v_cvt_pk_bf16_f32 v6, v6, v7
	v_cvt_pk_bf16_f32 v7, v8, v9
	global_store_dwordx2 v[2:3], v[4:5], off
	global_store_dwordx2 v[2:3], v[6:7], off offset:512
	s_waitcnt lgkmcnt(0)
	s_barrier
	s_and_saveexec_b64 s[42:43], s[4:5]
	s_xor_b64 s[42:43], exec, s[42:43]
	s_cbranch_execz .LBB0_1270
	v_mul_f32_e32 v2, 0x427c0000, v97
	v_mul_f32_e32 v3, 0x42780000, v97
	ds_read_u16 v4, v103 offset:33280
	ds_read_u16 v5, v103 offset:33808
	v_mul_f32_e32 v2, 0x3fb8aa3b, v2
	v_mul_f32_e32 v3, 0x3fb8aa3b, v3
	v_exp_f32_e32 v2, v2
	v_exp_f32_e32 v3, v3
	s_waitcnt lgkmcnt(0)
	v_lshlrev_b32_e32 v5, 16, v5
	v_lshlrev_b32_e32 v4, 16, v4
	ds_read_u16 v6, v103 offset:34336
	ds_read_u16 v7, v103 offset:34864
	v_pk_mul_f32 v[2:3], v[2:3], v[4:5]
	v_mul_f32_e32 v4, 0x42740000, v97
	v_mul_f32_e32 v5, 0x42700000, v97
	v_mul_f32_e32 v4, 0x3fb8aa3b, v4
	v_mul_f32_e32 v5, 0x3fb8aa3b, v5
	v_exp_f32_e32 v4, v4
	v_exp_f32_e32 v5, v5
	s_waitcnt lgkmcnt(0)
	v_lshlrev_b32_e32 v7, 16, v7
	v_lshlrev_b32_e32 v6, 16, v6
	ds_read_u16 v8, v103 offset:35392
	ds_read_u16 v9, v103 offset:35920
	v_pk_mul_f32 v[6:7], v[4:5], v[6:7]
	v_mul_f32_e32 v4, 0x426c0000, v97
	v_mul_f32_e32 v5, 0x42680000, v97
	v_mul_f32_e32 v4, 0x3fb8aa3b, v4
	v_mul_f32_e32 v5, 0x3fb8aa3b, v5
	v_exp_f32_e32 v4, v4
	v_exp_f32_e32 v5, v5
	s_waitcnt lgkmcnt(0)
	v_lshlrev_b32_e32 v9, 16, v9
	v_lshlrev_b32_e32 v8, 16, v8
	ds_read_u16 v10, v103 offset:36448
	ds_read_u16 v11, v103 offset:36976
	v_pk_mul_f32 v[8:9], v[4:5], v[8:9]
	v_mul_f32_e32 v4, 0x42640000, v97
	v_mul_f32_e32 v5, 0x42600000, v97
	v_mul_f32_e32 v4, 0x3fb8aa3b, v4
	v_mul_f32_e32 v5, 0x3fb8aa3b, v5
	v_exp_f32_e32 v4, v4
	v_exp_f32_e32 v5, v5
	s_waitcnt lgkmcnt(0)
	v_lshlrev_b32_e32 v11, 16, v11
	v_lshlrev_b32_e32 v10, 16, v10
	s_mov_b64 s[54:55], 0x8000
	v_pk_mul_f32 v[10:11], v[4:5], v[10:11]
	v_cvt_pk_bf16_f32 v5, v6, v7
	v_cvt_pk_bf16_f32 v6, v8, v9
	v_lshl_add_u64 v[8:9], v[62:63], 1, s[72:73]
	v_cvt_pk_bf16_f32 v4, v2, v3
	v_lshl_add_u64 v[2:3], v[8:9], 0, s[54:55]
	s_mov_b32 s54, 0x8000
	v_add_co_u32_e32 v8, vcc, s54, v8
	v_cvt_pk_bf16_f32 v7, v10, v11
	s_nop 0
	v_addc_co_u32_e32 v9, vcc, 0, v9, vcc
	global_store_dwordx4 v[8:9], v[4:7], off
	ds_read_u16 v6, v103 offset:37504
	ds_read_u16 v7, v103 offset:38032
	v_mul_f32_e32 v4, 0x425c0000, v97
	v_mul_f32_e32 v5, 0x42580000, v97
	v_mul_f32_e32 v4, 0x3fb8aa3b, v4
	v_mul_f32_e32 v5, 0x3fb8aa3b, v5
	v_exp_f32_e32 v4, v4
	v_exp_f32_e32 v5, v5
	s_waitcnt lgkmcnt(0)
; DI unsigned pk_bf16(float a, float b) { f32x2 v = {a, b}; bf2_t r = __builtin_convertvector(v, bf2_t); return __builtin_bit_cast(unsigned, r); }
; DI float bf2f(bf16_t b) { return __uint_as_float(((unsigned)b) << 16); }
; DI void phase_ret_prep(const Params& p, unsigned char* smem) {
;     ...
;             const int dk = tid - 256;
; #pragma unroll
;             for (int i0 = 0; i0 < 64; i0 += 8) { float v[8];
; #pragma unroll
;                 for (int j = 0; j < 8; ++j) v[j] = bf2f(kr[(i0 + j) * 264 + dk]) * __expf(lg * (float)(63 - i0 - j));
;                 u32x4 w; w.x = pk_bf16(v[0], v[1]); w.y = pk_bf16(v[2], v[3]); w.z = pk_bf16(v[4], v[5]); w.w = pk_bf16(v[6], v[7]);
;                 *(u32x4*)(o_kdT + ((((dk >> 5) * 4 + (i0 >> 4)) * 64 + (dk & 31) + 32 * ((i0 >> 3) & 1)) << 3)) = w; }
	v_lshlrev_b32_e32 v7, 16, v7
	v_lshlrev_b32_e32 v6, 16, v6
	ds_read_u16 v8, v103 offset:38560
	ds_read_u16 v9, v103 offset:39088
	v_pk_mul_f32 v[4:5], v[4:5], v[6:7]
	v_mul_f32_e32 v6, 0x42540000, v97
	v_mul_f32_e32 v7, 0x42500000, v97
	v_mul_f32_e32 v6, 0x3fb8aa3b, v6
	v_mul_f32_e32 v7, 0x3fb8aa3b, v7
	v_exp_f32_e32 v6, v6
	v_exp_f32_e32 v7, v7
	s_waitcnt lgkmcnt(0)
	v_lshlrev_b32_e32 v9, 16, v9
	v_lshlrev_b32_e32 v8, 16, v8
	ds_read_u16 v10, v103 offset:39616
	ds_read_u16 v11, v103 offset:40144
	v_pk_mul_f32 v[6:7], v[6:7], v[8:9]
	v_mul_f32_e32 v8, 0x424c0000, v97
	v_mul_f32_e32 v9, 0x42480000, v97
	v_mul_f32_e32 v8, 0x3fb8aa3b, v8
	v_mul_f32_e32 v9, 0x3fb8aa3b, v9
	v_exp_f32_e32 v8, v8
	v_exp_f32_e32 v9, v9
	s_waitcnt lgkmcnt(0)
	v_lshlrev_b32_e32 v11, 16, v11
	v_lshlrev_b32_e32 v10, 16, v10
	ds_read_u16 v12, v103 offset:40672
	ds_read_u16 v13, v103 offset:41200
	v_pk_mul_f32 v[8:9], v[8:9], v[10:11]
	v_mul_f32_e32 v10, 0x42440000, v97
	v_mul_f32_e32 v11, 0x42400000, v97
	v_mul_f32_e32 v10, 0x3fb8aa3b, v10
	v_mul_f32_e32 v11, 0x3fb8aa3b, v11
	v_exp_f32_e32 v10, v10
	v_exp_f32_e32 v11, v11
	s_waitcnt lgkmcnt(0)
	v_lshlrev_b32_e32 v13, 16, v13
	v_lshlrev_b32_e32 v12, 16, v12
	v_cvt_pk_bf16_f32 v4, v4, v5
	v_pk_mul_f32 v[10:11], v[10:11], v[12:13]
	v_cvt_pk_bf16_f32 v5, v6, v7
	v_cvt_pk_bf16_f32 v6, v8, v9
	v_cvt_pk_bf16_f32 v7, v10, v11
	global_store_dwordx4 v[2:3], v[4:7], off offset:512
	ds_read_u16 v6, v103 offset:41728
	ds_read_u16 v7, v103 offset:42256
	v_mul_f32_e32 v4, 0x423c0000, v97
	v_mul_f32_e32 v5, 0x42380000, v97
	v_mul_f32_e32 v4, 0x3fb8aa3b, v4
	v_mul_f32_e32 v5, 0x3fb8aa3b, v5
	v_exp_f32_e32 v4, v4
	v_exp_f32_e32 v5, v5
	s_waitcnt lgkmcnt(0)
	v_lshlrev_b32_e32 v7, 16, v7
	v_lshlrev_b32_e32 v6, 16, v6
	ds_read_u16 v8, v103 offset:42784
	ds_read_u16 v9, v103 offset:43312
	v_pk_mul_f32 v[4:5], v[4:5], v[6:7]
	v_mul_f32_e32 v6, 0x42340000, v97
	v_mul_f32_e32 v7, 0x42300000, v97
	v_mul_f32_e32 v6, 0x3fb8aa3b, v6
	v_mul_f32_e32 v7, 0x3fb8aa3b, v7
	v_exp_f32_e32 v6, v6
	v_exp_f32_e32 v7, v7
	s_waitcnt lgkmcnt(0)
	v_lshlrev_b32_e32 v9, 16, v9
	v_lshlrev_b32_e32 v8, 16, v8
	ds_read_u16 v10, v103 offset:43840
	ds_read_u16 v11, v103 offset:44368
	v_pk_mul_f32 v[6:7], v[6:7], v[8:9]
	v_mul_f32_e32 v8, 0x422c0000, v97
	v_mul_f32_e32 v9, 0x42280000, v97
	v_mul_f32_e32 v8, 0x3fb8aa3b, v8
	v_mul_f32_e32 v9, 0x3fb8aa3b, v9
	v_exp_f32_e32 v8, v8
	v_exp_f32_e32 v9, v9
	s_waitcnt lgkmcnt(0)
	v_lshlrev_b32_e32 v11, 16, v11
	v_lshlrev_b32_e32 v10, 16, v10
	ds_read_u16 v12, v103 offset:44896
	ds_read_u16 v13, v103 offset:45424
	v_pk_mul_f32 v[8:9], v[8:9], v[10:11]
	v_mul_f32_e32 v10, 0x42240000, v97
	v_mul_f32_e32 v11, 0x42200000, v97
	v_mul_f32_e32 v10, 0x3fb8aa3b, v10
	v_mul_f32_e32 v11, 0x3fb8aa3b, v11
	v_exp_f32_e32 v10, v10
	v_exp_f32_e32 v11, v11
	s_waitcnt lgkmcnt(0)
	v_lshlrev_b32_e32 v13, 16, v13
	v_lshlrev_b32_e32 v12, 16, v12
	v_cvt_pk_bf16_f32 v4, v4, v5
	v_pk_mul_f32 v[10:11], v[10:11], v[12:13]
	v_cvt_pk_bf16_f32 v5, v6, v7
	v_cvt_pk_bf16_f32 v6, v8, v9
	v_cvt_pk_bf16_f32 v7, v10, v11
	global_store_dwordx4 v[2:3], v[4:7], off offset:1024
	ds_read_u16 v6, v103 offset:45952
	ds_read_u16 v7, v103 offset:46480
	v_mul_f32_e32 v4, 0x421c0000, v97
	v_mul_f32_e32 v5, 0x42180000, v97
	v_mul_f32_e32 v4, 0x3fb8aa3b, v4
	v_mul_f32_e32 v5, 0x3fb8aa3b, v5
	v_exp_f32_e32 v4, v4
	v_exp_f32_e32 v5, v5
	s_waitcnt lgkmcnt(0)
	v_lshlrev_b32_e32 v7, 16, v7
	v_lshlrev_b32_e32 v6, 16, v6
	ds_read_u16 v8, v103 offset:47008
	ds_read_u16 v9, v103 offset:47536
	v_pk_mul_f32 v[4:5], v[4:5], v[6:7]
	v_mul_f32_e32 v6, 0x42140000, v97
	v_mul_f32_e32 v7, 0x42100000, v97
	v_mul_f32_e32 v6, 0x3fb8aa3b, v6
	v_mul_f32_e32 v7, 0x3fb8aa3b, v7
	v_exp_f32_e32 v6, v6
	v_exp_f32_e32 v7, v7
	s_waitcnt lgkmcnt(0)
	v_lshlrev_b32_e32 v9, 16, v9
	v_lshlrev_b32_e32 v8, 16, v8
	ds_read_u16 v10, v103 offset:48064
	ds_read_u16 v11, v103 offset:48592
	v_pk_mul_f32 v[6:7], v[6:7], v[8:9]
	v_mul_f32_e32 v8, 0x420c0000, v97
	v_mul_f32_e32 v9, 0x42080000, v97
	v_mul_f32_e32 v8, 0x3fb8aa3b, v8
	v_mul_f32_e32 v9, 0x3fb8aa3b, v9
	v_exp_f32_e32 v8, v8
	v_exp_f32_e32 v9, v9
	s_waitcnt lgkmcnt(0)
	v_lshlrev_b32_e32 v11, 16, v11
	v_lshlrev_b32_e32 v10, 16, v10
	ds_read_u16 v12, v103 offset:49120
	ds_read_u16 v13, v103 offset:49648
	v_pk_mul_f32 v[8:9], v[8:9], v[10:11]
	v_mul_f32_e32 v10, 0x42040000, v97
	v_mul_f32_e32 v11, 0x42000000, v97
	v_mul_f32_e32 v10, 0x3fb8aa3b, v10
	v_mul_f32_e32 v11, 0x3fb8aa3b, v11
	v_exp_f32_e32 v10, v10
	v_exp_f32_e32 v11, v11
	s_waitcnt lgkmcnt(0)
	v_lshlrev_b32_e32 v13, 16, v13
	v_lshlrev_b32_e32 v12, 16, v12
	v_cvt_pk_bf16_f32 v4, v4, v5
	v_pk_mul_f32 v[10:11], v[10:11], v[12:13]
	v_cvt_pk_bf16_f32 v5, v6, v7
	v_cvt_pk_bf16_f32 v6, v8, v9
	v_cvt_pk_bf16_f32 v7, v10, v11
	global_store_dwordx4 v[2:3], v[4:7], off offset:1536
	ds_read_u16 v6, v103 offset:50176
	ds_read_u16 v7, v103 offset:50704
	v_mul_f32_e32 v4, 0x41f80000, v97
	v_mul_f32_e32 v5, 0x41f00000, v97
	v_mul_f32_e32 v4, 0x3fb8aa3b, v4
	v_mul_f32_e32 v5, 0x3fb8aa3b, v5
	v_exp_f32_e32 v4, v4
	v_exp_f32_e32 v5, v5
	s_waitcnt lgkmcnt(0)
	v_lshlrev_b32_e32 v7, 16, v7
	v_lshlrev_b32_e32 v6, 16, v6
	ds_read_u16 v8, v103 offset:51232
	ds_read_u16 v9, v103 offset:51760
	v_pk_mul_f32 v[4:5], v[4:5], v[6:7]
	v_mul_f32_e32 v6, 0x41e80000, v97
	v_mul_f32_e32 v7, 0x41e00000, v97
	v_mul_f32_e32 v6, 0x3fb8aa3b, v6
	v_mul_f32_e32 v7, 0x3fb8aa3b, v7
	v_exp_f32_e32 v6, v6
	v_exp_f32_e32 v7, v7
	s_waitcnt lgkmcnt(0)
	v_lshlrev_b32_e32 v9, 16, v9
	v_lshlrev_b32_e32 v8, 16, v8
	ds_read_u16 v10, v103 offset:52288
	ds_read_u16 v11, v103 offset:52816
	v_pk_mul_f32 v[6:7], v[6:7], v[8:9]
	v_mul_f32_e32 v8, 0x41d80000, v97
	v_mul_f32_e32 v9, 0x41d00000, v97
	v_mul_f32_e32 v8, 0x3fb8aa3b, v8
	v_mul_f32_e32 v9, 0x3fb8aa3b, v9
	v_exp_f32_e32 v8, v8
	v_exp_f32_e32 v9, v9
	s_waitcnt lgkmcnt(0)
; DI unsigned pk_bf16(float a, float b) { f32x2 v = {a, b}; bf2_t r = __builtin_convertvector(v, bf2_t); return __builtin_bit_cast(unsigned, r); }
; DI float bf2f(bf16_t b) { return __uint_as_float(((unsigned)b) << 16); }
; DI void phase_ret_prep(const Params& p, unsigned char* smem) {
;     ...
;             const int dk = tid - 256;
; #pragma unroll
;             for (int i0 = 0; i0 < 64; i0 += 8) { float v[8];
; #pragma unroll
;                 for (int j = 0; j < 8; ++j) v[j] = bf2f(kr[(i0 + j) * 264 + dk]) * __expf(lg * (float)(63 - i0 - j));
;                 u32x4 w; w.x = pk_bf16(v[0], v[1]); w.y = pk_bf16(v[2], v[3]); w.z = pk_bf16(v[4], v[5]); w.w = pk_bf16(v[6], v[7]);
;                 *(u32x4*)(o_kdT + ((((dk >> 5) * 4 + (i0 >> 4)) * 64 + (dk & 31) + 32 * ((i0 >> 3) & 1)) << 3)) = w; }
	v_lshlrev_b32_e32 v11, 16, v11
	v_lshlrev_b32_e32 v10, 16, v10
	ds_read_u16 v12, v103 offset:53344
	ds_read_u16 v13, v103 offset:53872
	v_pk_mul_f32 v[8:9], v[8:9], v[10:11]
	v_mul_f32_e32 v10, 0x41c80000, v97
	v_mul_f32_e32 v11, 0x41c00000, v97
	v_mul_f32_e32 v10, 0x3fb8aa3b, v10
	v_mul_f32_e32 v11, 0x3fb8aa3b, v11
	v_exp_f32_e32 v10, v10
	v_exp_f32_e32 v11, v11
	s_waitcnt lgkmcnt(0)
	v_lshlrev_b32_e32 v13, 16, v13
	v_lshlrev_b32_e32 v12, 16, v12
	v_cvt_pk_bf16_f32 v4, v4, v5
	v_pk_mul_f32 v[10:11], v[10:11], v[12:13]
	v_cvt_pk_bf16_f32 v5, v6, v7
	v_cvt_pk_bf16_f32 v6, v8, v9
	v_cvt_pk_bf16_f32 v7, v10, v11
	global_store_dwordx4 v[2:3], v[4:7], off offset:2048
	ds_read_u16 v6, v103 offset:54400
	ds_read_u16 v7, v103 offset:54928
	v_mul_f32_e32 v4, 0x41b80000, v97
	v_mul_f32_e32 v5, 0x41b00000, v97
	v_mul_f32_e32 v4, 0x3fb8aa3b, v4
	v_mul_f32_e32 v5, 0x3fb8aa3b, v5
	v_exp_f32_e32 v4, v4
	v_exp_f32_e32 v5, v5
	s_waitcnt lgkmcnt(0)
	v_lshlrev_b32_e32 v7, 16, v7
	v_lshlrev_b32_e32 v6, 16, v6
	ds_read_u16 v8, v103 offset:55456
	ds_read_u16 v9, v103 offset:55984
	v_pk_mul_f32 v[4:5], v[4:5], v[6:7]
	v_mul_f32_e32 v6, 0x41a80000, v97
	v_mul_f32_e32 v7, 0x41a00000, v97
	v_mul_f32_e32 v6, 0x3fb8aa3b, v6
	v_mul_f32_e32 v7, 0x3fb8aa3b, v7
	v_exp_f32_e32 v6, v6
	v_exp_f32_e32 v7, v7
	s_waitcnt lgkmcnt(0)
	v_lshlrev_b32_e32 v9, 16, v9
	v_lshlrev_b32_e32 v8, 16, v8
	ds_read_u16 v10, v103 offset:56512
	ds_read_u16 v11, v103 offset:57040
	v_pk_mul_f32 v[6:7], v[6:7], v[8:9]
	v_mul_f32_e32 v8, 0x41980000, v97
	v_mul_f32_e32 v9, 0x41900000, v97
	v_mul_f32_e32 v8, 0x3fb8aa3b, v8
	v_mul_f32_e32 v9, 0x3fb8aa3b, v9
	v_exp_f32_e32 v8, v8
	v_exp_f32_e32 v9, v9
	s_waitcnt lgkmcnt(0)
	v_lshlrev_b32_e32 v11, 16, v11
	v_lshlrev_b32_e32 v10, 16, v10
	ds_read_u16 v12, v103 offset:57568
	ds_read_u16 v13, v103 offset:58096
	v_pk_mul_f32 v[8:9], v[8:9], v[10:11]
	v_mul_f32_e32 v10, 0x41880000, v97
	v_mul_f32_e32 v11, 0x41800000, v97
	v_mul_f32_e32 v10, 0x3fb8aa3b, v10
	v_mul_f32_e32 v11, 0x3fb8aa3b, v11
	v_exp_f32_e32 v10, v10
	v_exp_f32_e32 v11, v11
	s_waitcnt lgkmcnt(0)
	v_lshlrev_b32_e32 v13, 16, v13
	v_lshlrev_b32_e32 v12, 16, v12
	v_cvt_pk_bf16_f32 v4, v4, v5
	v_pk_mul_f32 v[10:11], v[10:11], v[12:13]
	v_cvt_pk_bf16_f32 v5, v6, v7
	v_cvt_pk_bf16_f32 v6, v8, v9
	v_cvt_pk_bf16_f32 v7, v10, v11
	global_store_dwordx4 v[2:3], v[4:7], off offset:2560
	ds_read_u16 v6, v103 offset:58624
	ds_read_u16 v7, v103 offset:59152
	v_mul_f32_e32 v4, 0x41700000, v97
	v_mul_f32_e32 v5, 0x41600000, v97
	v_mul_f32_e32 v4, 0x3fb8aa3b, v4
	v_mul_f32_e32 v5, 0x3fb8aa3b, v5
	v_exp_f32_e32 v4, v4
	v_exp_f32_e32 v5, v5
	s_waitcnt lgkmcnt(0)
	v_lshlrev_b32_e32 v7, 16, v7
	v_lshlrev_b32_e32 v6, 16, v6
	ds_read_u16 v8, v103 offset:59680
	ds_read_u16 v9, v103 offset:60208
	v_pk_mul_f32 v[4:5], v[4:5], v[6:7]
	v_mul_f32_e32 v6, 0x41500000, v97
	v_mul_f32_e32 v7, 0x41400000, v97
	v_mul_f32_e32 v6, 0x3fb8aa3b, v6
	v_mul_f32_e32 v7, 0x3fb8aa3b, v7
	v_exp_f32_e32 v6, v6
	v_exp_f32_e32 v7, v7
	s_waitcnt lgkmcnt(0)
	v_lshlrev_b32_e32 v9, 16, v9
	v_lshlrev_b32_e32 v8, 16, v8
	ds_read_u16 v10, v103 offset:60736
	ds_read_u16 v11, v103 offset:61264
	v_pk_mul_f32 v[6:7], v[6:7], v[8:9]
	v_mul_f32_e32 v8, 0x41300000, v97
	v_mul_f32_e32 v9, 0x41200000, v97
	v_mul_f32_e32 v8, 0x3fb8aa3b, v8
	v_mul_f32_e32 v9, 0x3fb8aa3b, v9
	v_exp_f32_e32 v8, v8
	v_exp_f32_e32 v9, v9
	s_waitcnt lgkmcnt(0)
	v_lshlrev_b32_e32 v11, 16, v11
	v_lshlrev_b32_e32 v10, 16, v10
	ds_read_u16 v12, v103 offset:61792
	ds_read_u16 v13, v103 offset:62320
	v_pk_mul_f32 v[8:9], v[8:9], v[10:11]
	v_mul_f32_e32 v10, 0x41100000, v97
	v_mul_f32_e32 v11, 0x41000000, v97
	v_mul_f32_e32 v10, 0x3fb8aa3b, v10
	v_mul_f32_e32 v11, 0x3fb8aa3b, v11
	v_exp_f32_e32 v10, v10
	v_exp_f32_e32 v11, v11
	s_waitcnt lgkmcnt(0)
	v_lshlrev_b32_e32 v13, 16, v13
	v_lshlrev_b32_e32 v12, 16, v12
	v_cvt_pk_bf16_f32 v4, v4, v5
	v_pk_mul_f32 v[10:11], v[10:11], v[12:13]
	v_cvt_pk_bf16_f32 v5, v6, v7
	v_cvt_pk_bf16_f32 v6, v8, v9
	v_cvt_pk_bf16_f32 v7, v10, v11
	global_store_dwordx4 v[2:3], v[4:7], off offset:3072
	ds_read_u16 v6, v103 offset:62848
	ds_read_u16 v7, v103 offset:63376
	v_mul_f32_e32 v4, 0x40e00000, v97
	v_mul_f32_e32 v5, 0x40c00000, v97
	v_mul_f32_e32 v4, 0x3fb8aa3b, v4
	v_mul_f32_e32 v5, 0x3fb8aa3b, v5
	v_exp_f32_e32 v4, v4
	v_exp_f32_e32 v5, v5
	s_waitcnt lgkmcnt(0)
	v_lshlrev_b32_e32 v7, 16, v7
	v_lshlrev_b32_e32 v6, 16, v6
	ds_read_u16 v8, v103 offset:63904
	ds_read_u16 v9, v103 offset:64432
	v_pk_mul_f32 v[4:5], v[4:5], v[6:7]
	v_mul_f32_e32 v6, 0x40a00000, v97
	v_mul_f32_e32 v7, 4.0, v97
	v_mul_f32_e32 v6, 0x3fb8aa3b, v6
	v_mul_f32_e32 v7, 0x3fb8aa3b, v7
	v_exp_f32_e32 v6, v6
	v_exp_f32_e32 v7, v7
	s_waitcnt lgkmcnt(0)
	v_lshlrev_b32_e32 v9, 16, v9
	v_lshlrev_b32_e32 v8, 16, v8
	ds_read_u16 v10, v103 offset:64960
	ds_read_u16 v11, v103 offset:65488
	v_pk_mul_f32 v[6:7], v[6:7], v[8:9]
	v_mul_f32_e32 v8, 0x40400000, v97
	v_add_f32_e32 v9, v97, v97
	v_mul_f32_e32 v8, 0x3fb8aa3b, v8
	v_mul_f32_e32 v9, 0x3fb8aa3b, v9
	v_exp_f32_e32 v8, v8
	v_exp_f32_e32 v9, v9
	s_waitcnt lgkmcnt(0)
	v_lshlrev_b32_e32 v11, 16, v11
	v_lshlrev_b32_e32 v10, 16, v10
	ds_read_u16 v12, v104 offset:32736
	ds_read_u16 v13, v104 offset:33264
	v_pk_mul_f32 v[8:9], v[8:9], v[10:11]
	v_mul_f32_e32 v11, 0, v97
	v_mul_f32_e32 v10, 0x3fb8aa3b, v97
	v_mul_f32_e32 v11, 0x3fb8aa3b, v11
	v_exp_f32_e32 v10, v10
	v_exp_f32_e32 v11, v11
	s_waitcnt lgkmcnt(0)
	v_lshlrev_b32_e32 v13, 16, v13
	v_lshlrev_b32_e32 v12, 16, v12
	v_cvt_pk_bf16_f32 v4, v4, v5
	v_pk_mul_f32 v[10:11], v[10:11], v[12:13]
	v_cvt_pk_bf16_f32 v5, v6, v7
	v_cvt_pk_bf16_f32 v6, v8, v9
	v_cvt_pk_bf16_f32 v7, v10, v11
	global_store_dwordx4 v[2:3], v[4:7], off offset:3584
